# v31: v30 + prologue->in-proj seam split (arrive after weight copies, group-local layer-0 row norm as filler, group wait + TOP0)
# baseline (speedup 1.0000x reference)
; __device__ __forceinline__ int opaque_tid(int wv) { unsigned z = 0u; asm volatile("" : "+v"(z)); return (wv << 6) | (int)__builtin_amdgcn_mbcnt_hi(~0u, __builtin_amdgcn_mbcnt_lo(~0u, z)); }
; #define SEAM(k) do { } while (0)
; #define SEAM(k) do { if (lo <= (k) && (k) + 1 < hi) { if (hi > 1000) grid.sync(); else xcd_barrier(xbar, xst, opaque_tid(wv) == 0); } } while (0)
; __global__ void __launch_bounds__(512) fwd_megakernel(Args A) {
;     ...
;     if (EN(0) && IN(0)) {
;         prologue_phase(A, lds, G, wv);
;         if (opaque_tid(wv) == 0) { unsigned sp = 0u; while (__hip_atomic_load((unsigned*)(ws + WS_CTL) + 4, __ATOMIC_RELAXED, __HIP_MEMORY_SCOPE_AGENT) < 384u && ++sp < (1u << 22)) __builtin_amdgcn_s_sleep(2); }
;         __syncthreads();
;         __builtin_amdgcn_fence(__ATOMIC_ACQUIRE, "agent");
;         norm_mod_phase(A.x, A.norm_mix, mod, mod + DM, Hb, G, wv);
;         SEAM(0);
.LBB0_111:
	s_or_b64 exec, exec, s[0:1]
	s_barrier
	s_waitcnt vmcnt(0)
	buffer_inv sc1
	s_mov_b64 s[12:13], exec
	s_mov_b64 exec, 1
	s_and_b32 s4, s86, 7
	s_lshl_b32 s4, s4, 8
	s_add_u32 s4, s4, 0x6000
	s_add_u32 s4, s60, s4
	s_addc_u32 s5, s61, 0
	v_mov_b32_e32 v4, 0
	global_load_dword v5, v4, s[4:5] sc1
	s_waitcnt vmcnt(0)
	v_readfirstlane_b32 s6, v5
	s_mov_b64 exec, s[12:13]
	s_bcnt1_i32_b32 s6, s6
	v_readlane_b32 s7, v251, 2
	s_mov_b32 s100, 0
	s_mov_b32 s101, 0
	s_cmpk_lg_i32 s7, 0x100
	s_cbranch_scc1 .Lm0_done
	s_mov_b32 s100, 1
	s_cmp_lg_u32 s6, 1
	s_cbranch_scc1 .Lm0_done
	s_mov_b32 s100, 2
.Lm0_done:
	s_cmp_eq_u32 s100, 0
	s_cbranch_scc1 .Ls0a_skip
	s_waitcnt vmcnt(0) lgkmcnt(0)
	s_barrier
	s_cmp_lg_u32 s94, 0
	s_cbranch_scc1 .Ls0a_skip
	s_mov_b64 exec, 1
	v_mov_b32_e32 v4, 1
	v_mov_b32_e32 v8, 0
	s_and_b32 s6, s86, 7
	s_lshl_b32 s6, s6, 6
	s_add_u32 s6, s6, 0x6e00
	s_add_u32 s10, s60, s6
	s_addc_u32 s11, s61, 0
	s_add_u32 s8, s60, 0x6c80
	s_addc_u32 s9, s61, 0
	s_cmp_eq_u32 s100, 2
	s_cbranch_scc1 .Ls0a_arr
	buffer_wbl2 sc1
	s_waitcnt vmcnt(0)
.Ls0a_arr:
	global_atomic_add v6, v8, v4, s[10:11] sc0
	s_waitcnt vmcnt(0)
	v_readfirstlane_b32 s15, v6
	s_nop 1
	s_cmp_eq_u32 s15, 31
	s_cbranch_scc0 .Ls0a_done
	s_cmp_lg_u32 s100, 2
	s_cbranch_scc1 .Ls0a_top
	buffer_wbl2 sc1
	s_waitcnt vmcnt(0)

; __device__ __forceinline__ unsigned cvt_pk_bf16(float lo, float hi) { const f32x2 v = {lo, hi}; const bf16x2_t b = __builtin_convertvector(v, bf16x2_t); return __builtin_bit_cast(unsigned, b); }
; __device__ __forceinline__ int opaque_tid(int wv) { unsigned z = 0u; asm volatile("" : "+v"(z)); return (wv << 6) | (int)__builtin_amdgcn_mbcnt_hi(~0u, __builtin_amdgcn_mbcnt_lo(~0u, z)); }
; __device__ __forceinline__ void norm_mod_phase(const float* __restrict__ X, const float* __restrict__ g, const float* __restrict__ sh, const float* __restrict__ sc, bf16_t* __restrict__ H, int G, const int wv) {
;     const int tid = opaque_tid(wv), lane = tid & 63, gw = blockIdx.x * 8 + (tid >> 6), NGW = G * 8;
;     for (int row = gw; row < MTOK; row += NGW) {
;         const int bb = row >> 11;
;         const f32x4* xr = (const f32x4*)(X + (size_t)row * DM) + lane;
;         f32x4 v[8]; float ss = 0.f;
; #pragma unroll
;         for (int j = 0; j < 8; ++j) { v[j] = xr[64 * j]; ss += (v[j][0] * v[j][0] + v[j][1] * v[j][1]) + (v[j][2] * v[j][2] + v[j][3] * v[j][3]); }
;         const float rinv = 1.0f / sqrtf(wave_sum(ss, lane) * (1.0f / DM) + EPS);
;         u32x2* op = (u32x2*)(H + (size_t)row * DM) + lane;
; #pragma unroll
;         for (int j = 0; j < 8; ++j) { const int c = (lane + 64 * j) * 4;
;             const f32x4 gg = *(const f32x4*)(g + c), s1 = *(const f32x4*)(sc + (size_t)bb * ADAW + c), s0 = *(const f32x4*)(sh + (size_t)bb * ADAW + c);
;             const f32x4 y = v[j] * rinv * gg * (s1 + 1.0f) + s0;
;             u32x2 w; w.x = cvt_pk_bf16(y[0], y[1]); w.y = cvt_pk_bf16(y[2], y[3]); op[64 * j] = w; }
;     }
.Ls0a_skip:
	s_movk_i32 s0, 0x2000
	v_mbcnt_lo_u32_b32 v2, -1, v2
	v_mbcnt_hi_u32_b32 v2, -1, v2
	v_or_b32_e32 v3, s22, v2
	v_ashrrev_i32_e32 v3, 6, v3
	v_add_u32_e32 v66, s3, v3
	s_cmp_eq_u32 s100, 0
	s_cbranch_scc1 .Lnm_keep
	s_lshr_b32 s12, s86, 3
	s_and_b32 s13, s86, 7
	v_lshl_add_u32 v66, s12, 3, v3
	v_lshlrev_b32_e32 v66, 2, v66
	s_lshl_b32 s13, s13, 10
	v_add_u32_e32 v66, s13, v66
	s_mov_b32 s2, 1
.Lnm_keep:
	v_cmp_gt_i32_e32 vcc, s0, v66
	s_and_saveexec_b64 s[4:5], vcc
	v_readlane_b32 s16, v251, 21
	v_readlane_b32 s17, v251, 22
	s_cbranch_execz .LBB0_114
	v_and_b32_e32 v35, 63, v2
	v_lshlrev_b32_e32 v34, 2, v35
	v_lshlrev_b32_e32 v37, 4, v35
	global_load_dwordx4 v[2:5], v37, s[48:49]
	global_load_dwordx4 v[6:9], v37, s[48:49] offset:1024
	global_load_dwordx4 v[10:13], v37, s[48:49] offset:2048
	global_load_dwordx4 v[14:17], v37, s[48:49] offset:3072
	v_or_b32_e32 v36, 0x400, v34
	v_or_b32_e32 v38, 0x500, v34
	v_or_b32_e32 v40, 0x600, v34
	v_lshlrev_b32_e32 v26, 2, v36
	v_lshlrev_b32_e32 v27, 2, v38
	v_lshlrev_b32_e32 v39, 2, v40
	v_or_b32_e32 v42, 0x700, v34
	global_load_dwordx4 v[18:21], v26, s[48:49]
	global_load_dwordx4 v[22:25], v27, s[48:49]
	v_lshlrev_b32_e32 v41, 2, v42
	global_load_dwordx4 v[26:29], v39, s[48:49]
	global_load_dwordx4 v[30:33], v41, s[48:49]
	v_ashrrev_i32_e32 v67, 31, v66
	v_lshlrev_b64 v[44:45], 13, v[66:67]
	v_or_b32_e32 v44, v44, v37
	v_lshl_add_u64 v[44:45], s[40:41], 0, v[44:45]
	s_mov_b64 s[0:1], 0x1000
	v_lshl_add_u64 v[70:71], v[44:45], 0, s[0:1]
	v_lshlrev_b64 v[44:45], 12, v[66:67]
	s_add_u32 s6, s60, 0x202000
	v_lshl_or_b32 v44, v35, 3, v44
	s_addc_u32 s7, s61, 0
	s_ashr_i32 s3, s2, 31
	v_lshl_add_u64 v[44:45], s[60:61], 0, v[44:45]
	s_mov_b64 s[0:1], 0xc000000
	v_xor_b32_e32 v82, 4, v34
	v_xor_b32_e32 v83, 8, v34
	v_xor_b32_e32 v84, 16, v34
	v_xor_b32_e32 v85, 32, v34
	v_xor_b32_e32 v86, 64, v34
	v_xor_b32_e32 v87, 0x80, v34
	v_mov_b32_e32 v69, 0
	s_lshl_b64 s[8:9], s[2:3], 13
	v_lshl_add_u64 v[72:73], v[44:45], 0, s[0:1]
	s_lshl_b64 s[10:11], s[2:3], 12
	s_mov_b64 s[12:13], 0
	v_mov_b32_e32 v67, 0x358637bd
	s_mov_b32 s3, 0xf800000
	v_mov_b32_e32 v88, 0x260
	v_lshlrev_b32_e32 v68, 2, v34
	v_lshlrev_b32_e32 v74, 2, v36
	v_lshlrev_b32_e32 v76, 2, v38
	v_lshlrev_b32_e32 v78, 2, v40
	v_lshlrev_b32_e32 v80, 2, v42
	s_movk_i32 s14, 0x1fff
	s_cmp_eq_u32 s100, 0
	s_cbranch_scc1 .Lnm_keep2
	v_readfirstlane_b32 s14, v66
	s_add_u32 s14, s14, 3
.Lnm_keep2:
.LBB0_113:
	global_load_dwordx4 v[34:37], v[70:71], off offset:-2048
	global_load_dwordx4 v[38:41], v[70:71], off offset:1024
	global_load_dwordx4 v[50:53], v[70:71], off offset:-4096
	global_load_dwordx4 v[46:49], v[70:71], off offset:-3072
	global_load_dwordx4 v[42:45], v[70:71], off offset:-1024
	global_load_dwordx4 v[54:57], v[70:71], off
	global_load_dwordx4 v[58:61], v[70:71], off offset:2048
	global_load_dwordx4 v[62:65], v[70:71], off offset:3072
	v_ashrrev_i32_e32 v89, 11, v66
	v_mul_hi_i32_i24_e32 v91, 0x3000, v89
	v_mul_i32_i24_e32 v90, 0x3000, v89
	v_lshlrev_b64 v[90:91], 2, v[90:91]
	v_mov_b32_e32 v75, v69
	v_mov_b32_e32 v77, v69
	v_mov_b32_e32 v79, v69
	v_mov_b32_e32 v81, v69
	v_lshl_add_u64 v[92:93], s[6:7], 0, v[90:91]
	v_lshl_add_u64 v[90:91], s[16:17], 0, v[90:91]
	v_lshl_add_u64 v[110:111], v[92:93], 0, v[68:69]
	v_lshl_add_u64 v[134:135], v[90:91], 0, v[68:69]
	v_lshl_add_u64 v[112:113], v[92:93], 0, v[74:75]
	v_lshl_add_u64 v[138:139], v[90:91], 0, v[74:75]
	v_lshl_add_u64 v[114:115], v[92:93], 0, v[76:77]
	v_lshl_add_u64 v[142:143], v[90:91], 0, v[76:77]
	v_lshl_add_u64 v[116:117], v[92:93], 0, v[78:79]
	v_lshl_add_u64 v[146:147], v[90:91], 0, v[78:79]
	v_lshl_add_u64 v[118:119], v[92:93], 0, v[80:81]
	v_lshl_add_u64 v[150:151], v[90:91], 0, v[80:81]
	global_load_dwordx4 v[90:93], v[110:111], off
	global_load_dwordx4 v[94:97], v[110:111], off offset:1024
	global_load_dwordx4 v[98:101], v[110:111], off offset:2048
	global_load_dwordx4 v[102:105], v[110:111], off offset:3072
	global_load_dwordx4 v[106:109], v[112:113], off
	s_nop 0
	global_load_dwordx4 v[110:113], v[114:115], off
	s_nop 0
	global_load_dwordx4 v[114:117], v[116:117], off
	s_nop 0
	global_load_dwordx4 v[118:121], v[118:119], off
	s_nop 0
	global_load_dwordx4 v[122:125], v[134:135], off
	global_load_dwordx4 v[126:129], v[134:135], off offset:1024
	global_load_dwordx4 v[130:133], v[134:135], off offset:2048
	s_nop 0
	global_load_dwordx4 v[134:137], v[134:135], off offset:3072
	s_nop 0
	global_load_dwordx4 v[138:141], v[138:139], off
	s_nop 0
	global_load_dwordx4 v[142:145], v[142:143], off
	s_nop 0
	global_load_dwordx4 v[146:149], v[146:147], off
	s_nop 0
	global_load_dwordx4 v[150:153], v[150:151], off
	v_add_u32_e32 v66, s2, v66
	v_cmp_lt_i32_e32 vcc, s14, v66
	s_or_b64 s[12:13], vcc, s[12:13]
	v_lshl_add_u64 v[70:71], v[70:71], 0, s[8:9]
	s_waitcnt vmcnt(23)
	v_pk_mul_f32 v[154:155], v[36:37], v[36:37]
	v_pk_mul_f32 v[156:157], v[34:35], v[34:35]
	s_waitcnt vmcnt(22)
	v_pk_mul_f32 v[158:159], v[40:41], v[40:41]
	v_pk_mul_f32 v[160:161], v[38:39], v[38:39]
	s_waitcnt vmcnt(21)
	v_mov_b32_e32 v164, v51
	s_waitcnt vmcnt(20)
	v_mov_b32_e32 v165, v47
	v_mov_b32_e32 v168, v53
	v_mov_b32_e32 v169, v49
	v_mov_b32_e32 v162, v50
	v_mov_b32_e32 v163, v46
	v_mov_b32_e32 v166, v52
	v_mov_b32_e32 v167, v48
	v_pk_mov_b32 v[178:179], v[156:157], v[154:155] op_sel:[1,0]
	v_mov_b32_e32 v157, v155
	v_pk_mov_b32 v[154:155], v[160:161], v[158:159] op_sel:[1,0]
	v_mov_b32_e32 v161, v159
	v_pk_mul_f32 v[158:159], v[164:165], v[164:165]
	v_pk_mul_f32 v[164:165], v[168:169], v[168:169]
	v_pk_fma_f32 v[158:159], v[162:163], v[162:163], v[158:159]
	v_pk_fma_f32 v[162:163], v[166:167], v[166:167], v[164:165]
	s_waitcnt vmcnt(19)
; __device__ __forceinline__ void norm_mod_phase(const float* __restrict__ X, const float* __restrict__ g, const float* __restrict__ sh, const float* __restrict__ sc, bf16_t* __restrict__ H, int G, const int wv) {
;     ...
;     for (int row = gw; row < MTOK; row += NGW) {
;         const int bb = row >> 11;
;         const f32x4* xr = (const f32x4*)(X + (size_t)row * DM) + lane;
;         f32x4 v[8]; float ss = 0.f;
; #pragma unroll
;         for (int j = 0; j < 8; ++j) { v[j] = xr[64 * j]; ss += (v[j][0] * v[j][0] + v[j][1] * v[j][1]) + (v[j][2] * v[j][2] + v[j][3] * v[j][3]); }
;         const float rinv = 1.0f / sqrtf(wave_sum(ss, lane) * (1.0f / DM) + EPS);
	v_mul_f32_e32 v170, v43, v43
	v_mul_f32_e32 v172, v45, v45
	v_pk_add_f32 v[156:157], v[178:179], v[156:157]
	v_pk_add_f32 v[158:159], v[158:159], v[162:163]
	s_waitcnt vmcnt(18)
	v_mul_f32_e32 v75, v56, v56
	v_mul_f32_e32 v77, v57, v57
	v_mul_f32_e32 v89, v55, v55
	v_mul_f32_e32 v177, v54, v54
	v_pk_fma_f32 v[168:169], v[42:43], v[42:43], v[170:171] op_sel_hi:[1,1,0]
	v_pk_fma_f32 v[170:171], v[44:45], v[44:45], v[172:173] op_sel_hi:[1,1,0]
	v_pk_add_f32 v[156:157], v[156:157], v[156:157] op_sel:[0,1] op_sel_hi:[1,0]
	v_pk_add_f32 v[158:159], v[158:159], v[158:159] op_sel:[0,1] op_sel_hi:[1,0]
	v_mov_b32_e32 v169, v75
	v_mov_b32_e32 v171, v77
	v_mov_b32_e32 v157, v89
	v_mov_b32_e32 v159, v177
	v_pk_add_f32 v[154:155], v[154:155], v[160:161]
	v_pk_add_f32 v[160:161], v[168:169], v[170:171]
	v_pk_add_f32 v[156:157], v[158:159], v[156:157]
	s_waitcnt vmcnt(17)
	v_mul_f32_e32 v174, v59, v59
	v_mul_f32_e32 v176, v61, v61
	v_pk_add_f32 v[156:157], v[156:157], v[160:161]
	s_waitcnt vmcnt(16)
	v_mul_f32_e32 v79, v64, v64
	v_mul_f32_e32 v81, v65, v65
	v_mul_f32_e32 v180, v63, v63
	v_mul_f32_e32 v181, v62, v62
	v_pk_fma_f32 v[172:173], v[58:59], v[58:59], v[174:175] op_sel_hi:[1,1,0]
	v_pk_fma_f32 v[174:175], v[60:61], v[60:61], v[176:177] op_sel_hi:[1,1,0]
	v_pk_add_f32 v[154:155], v[154:155], v[154:155] op_sel:[0,1] op_sel_hi:[1,0]
	v_pk_add_f32 v[156:157], v[156:157], v[156:157] op_sel:[0,1] op_sel_hi:[1,0]
	v_mov_b32_e32 v173, v79
	v_mov_b32_e32 v175, v81
	v_mov_b32_e32 v155, v180
	v_mov_b32_e32 v157, v181
	v_pk_add_f32 v[162:163], v[172:173], v[174:175]
	v_pk_add_f32 v[154:155], v[156:157], v[154:155]
	s_waitcnt vmcnt(15)
	v_pk_add_f32 v[92:93], v[92:93], 1.0 op_sel_hi:[1,0]
	v_pk_add_f32 v[154:155], v[154:155], v[162:163]
	v_pk_add_f32 v[90:91], v[90:91], 1.0 op_sel_hi:[1,0]
	v_add_f32_e32 v75, v154, v155
	ds_bpermute_b32 v77, v82, v75
	s_waitcnt vmcnt(14)
	v_pk_add_f32 v[96:97], v[96:97], 1.0 op_sel_hi:[1,0]
	v_pk_add_f32 v[94:95], v[94:95], 1.0 op_sel_hi:[1,0]
	s_waitcnt vmcnt(13)
	v_pk_add_f32 v[100:101], v[100:101], 1.0 op_sel_hi:[1,0]
	v_pk_add_f32 v[98:99], v[98:99], 1.0 op_sel_hi:[1,0]
	s_waitcnt lgkmcnt(0)
	v_add_f32_e32 v75, v75, v77
	ds_bpermute_b32 v77, v83, v75
	s_waitcnt vmcnt(12)
	v_pk_add_f32 v[104:105], v[104:105], 1.0 op_sel_hi:[1,0]
	v_pk_add_f32 v[102:103], v[102:103], 1.0 op_sel_hi:[1,0]
	s_waitcnt vmcnt(11)
	v_pk_add_f32 v[108:109], v[108:109], 1.0 op_sel_hi:[1,0]
	v_pk_add_f32 v[106:107], v[106:107], 1.0 op_sel_hi:[1,0]
	s_waitcnt lgkmcnt(0)
	v_add_f32_e32 v75, v75, v77
	ds_bpermute_b32 v77, v84, v75
	s_waitcnt vmcnt(10)
	v_pk_add_f32 v[112:113], v[112:113], 1.0 op_sel_hi:[1,0]
	v_pk_add_f32 v[110:111], v[110:111], 1.0 op_sel_hi:[1,0]
	s_waitcnt vmcnt(9)
	v_pk_add_f32 v[116:117], v[116:117], 1.0 op_sel_hi:[1,0]
	v_pk_add_f32 v[114:115], v[114:115], 1.0 op_sel_hi:[1,0]
	s_waitcnt lgkmcnt(0)
	v_add_f32_e32 v75, v75, v77
	ds_bpermute_b32 v77, v85, v75
	s_waitcnt vmcnt(8)
	v_pk_add_f32 v[120:121], v[120:121], 1.0 op_sel_hi:[1,0]
	v_pk_add_f32 v[118:119], v[118:119], 1.0 op_sel_hi:[1,0]
	s_waitcnt lgkmcnt(0)
	v_add_f32_e32 v75, v75, v77
	ds_bpermute_b32 v77, v86, v75
	s_waitcnt lgkmcnt(0)
	v_add_f32_e32 v75, v75, v77
	ds_bpermute_b32 v77, v87, v75
	s_waitcnt lgkmcnt(0)
; __device__ __forceinline__ unsigned cvt_pk_bf16(float lo, float hi) { const f32x2 v = {lo, hi}; const bf16x2_t b = __builtin_convertvector(v, bf16x2_t); return __builtin_bit_cast(unsigned, b); }
; __device__ __forceinline__ int opaque_tid(int wv) { unsigned z = 0u; asm volatile("" : "+v"(z)); return (wv << 6) | (int)__builtin_amdgcn_mbcnt_hi(~0u, __builtin_amdgcn_mbcnt_lo(~0u, z)); }
; #define SEAM(k) do { } while (0)
; #define SEAM(k) do { if (lo <= (k) && (k) + 1 < hi) { if (hi > 1000) grid.sync(); else xcd_barrier(xbar, xst, opaque_tid(wv) == 0); } } while (0)
; __device__ __forceinline__ void norm_mod_phase(const float* __restrict__ X, const float* __restrict__ g, const float* __restrict__ sh, const float* __restrict__ sc, bf16_t* __restrict__ H, int G, const int wv) {
;     ...
;         const float rinv = 1.0f / sqrtf(wave_sum(ss, lane) * (1.0f / DM) + EPS);
;         u32x2* op = (u32x2*)(H + (size_t)row * DM) + lane;
; #pragma unroll
;         for (int j = 0; j < 8; ++j) { const int c = (lane + 64 * j) * 4;
;             const f32x4 gg = *(const f32x4*)(g + c), s1 = *(const f32x4*)(sc + (size_t)bb * ADAW + c), s0 = *(const f32x4*)(sh + (size_t)bb * ADAW + c);
;             const f32x4 y = v[j] * rinv * gg * (s1 + 1.0f) + s0;
;             u32x2 w; w.x = cvt_pk_bf16(y[0], y[1]); w.y = cvt_pk_bf16(y[2], y[3]); op[64 * j] = w; }
; __global__ void __launch_bounds__(512) fwd_megakernel(Args A) {
;     ...
;     if (EN(0) && IN(0)) {
;         prologue_phase(A, lds, G, wv);
;         if (opaque_tid(wv) == 0) { unsigned sp = 0u; while (__hip_atomic_load((unsigned*)(ws + WS_CTL) + 4, __ATOMIC_RELAXED, __HIP_MEMORY_SCOPE_AGENT) < 384u && ++sp < (1u << 22)) __builtin_amdgcn_s_sleep(2); }
;         __syncthreads();
;         __builtin_amdgcn_fence(__ATOMIC_ACQUIRE, "agent");
;         norm_mod_phase(A.x, A.norm_mix, mod, mod + DM, Hb, G, wv);
;         SEAM(0);
	v_add_f32_e32 v75, v75, v77
	v_fmamk_f32 v75, v75, 0x3a000000, v67
	v_mul_f32_e32 v77, 0x4f800000, v75
	v_cmp_gt_f32_e32 vcc, s3, v75
	s_nop 1
	v_cndmask_b32_e32 v75, v75, v77, vcc
	v_sqrt_f32_e32 v77, v75
	s_nop 0
	v_add_u32_e32 v79, -1, v77
	v_add_u32_e32 v81, 1, v77
	v_fma_f32 v89, -v79, v77, v75
	v_fma_f32 v154, -v81, v77, v75
	v_cmp_ge_f32_e64 s[0:1], 0, v89
	s_nop 1
	v_cndmask_b32_e64 v77, v77, v79, s[0:1]
	v_cmp_lt_f32_e64 s[0:1], 0, v154
	s_nop 1
	v_cndmask_b32_e64 v77, v77, v81, s[0:1]
	v_mul_f32_e32 v79, 0x37800000, v77
	v_cndmask_b32_e32 v77, v77, v79, vcc
	v_cmp_class_f32_e32 vcc, v75, v88
	s_nop 1
	v_cndmask_b32_e32 v75, v77, v75, vcc
	v_div_scale_f32 v77, s[0:1], v75, v75, 1.0
	v_rcp_f32_e32 v81, v77
	v_div_scale_f32 v79, vcc, 1.0, v75, 1.0
	v_fma_f32 v89, -v77, v81, 1.0
	v_fmac_f32_e32 v81, v89, v81
	v_mul_f32_e32 v89, v79, v81
	v_fma_f32 v154, -v77, v89, v79
	v_fmac_f32_e32 v89, v154, v81
	v_fma_f32 v77, -v77, v89, v79
	v_div_fmas_f32 v77, v77, v81, v89
	v_div_fixup_f32 v154, v77, v75, 1.0
	v_pk_mul_f32 v[52:53], v[52:53], v[154:155] op_sel_hi:[1,0]
	v_pk_mul_f32 v[50:51], v[50:51], v[154:155] op_sel_hi:[1,0]
	v_pk_mul_f32 v[48:49], v[48:49], v[154:155] op_sel_hi:[1,0]
	v_pk_mul_f32 v[46:47], v[46:47], v[154:155] op_sel_hi:[1,0]
	v_pk_mul_f32 v[36:37], v[36:37], v[154:155] op_sel_hi:[1,0]
	v_pk_mul_f32 v[34:35], v[34:35], v[154:155] op_sel_hi:[1,0]
	v_pk_mul_f32 v[44:45], v[44:45], v[154:155] op_sel_hi:[1,0]
	v_pk_mul_f32 v[42:43], v[42:43], v[154:155] op_sel_hi:[1,0]
	v_pk_mul_f32 v[56:57], v[56:57], v[154:155] op_sel_hi:[1,0]
	v_pk_mul_f32 v[54:55], v[54:55], v[154:155] op_sel_hi:[1,0]
	v_pk_mul_f32 v[40:41], v[40:41], v[154:155] op_sel_hi:[1,0]
	v_pk_mul_f32 v[38:39], v[38:39], v[154:155] op_sel_hi:[1,0]
	v_pk_mul_f32 v[60:61], v[60:61], v[154:155] op_sel_hi:[1,0]
	v_pk_mul_f32 v[58:59], v[58:59], v[154:155] op_sel_hi:[1,0]
	v_pk_mul_f32 v[64:65], v[64:65], v[154:155] op_sel_hi:[1,0]
	v_pk_mul_f32 v[62:63], v[62:63], v[154:155] op_sel_hi:[1,0]
	v_pk_mul_f32 v[52:53], v[4:5], v[52:53]
	v_pk_mul_f32 v[50:51], v[2:3], v[50:51]
	v_pk_mul_f32 v[48:49], v[8:9], v[48:49]
	v_pk_mul_f32 v[46:47], v[6:7], v[46:47]
	v_pk_mul_f32 v[36:37], v[12:13], v[36:37]
	v_pk_mul_f32 v[34:35], v[10:11], v[34:35]
	v_pk_mul_f32 v[44:45], v[16:17], v[44:45]
	v_pk_mul_f32 v[42:43], v[14:15], v[42:43]
	v_pk_mul_f32 v[56:57], v[20:21], v[56:57]
	v_pk_mul_f32 v[54:55], v[18:19], v[54:55]
	v_pk_mul_f32 v[40:41], v[24:25], v[40:41]
	v_pk_mul_f32 v[38:39], v[22:23], v[38:39]
	v_pk_mul_f32 v[60:61], v[28:29], v[60:61]
	v_pk_mul_f32 v[58:59], v[26:27], v[58:59]
	v_pk_mul_f32 v[64:65], v[32:33], v[64:65]
	v_pk_mul_f32 v[62:63], v[30:31], v[62:63]
	s_waitcnt vmcnt(7)
	v_pk_fma_f32 v[52:53], v[92:93], v[52:53], v[124:125]
	v_pk_fma_f32 v[50:51], v[90:91], v[50:51], v[122:123]
	s_waitcnt vmcnt(6)
	v_pk_fma_f32 v[48:49], v[96:97], v[48:49], v[128:129]
	v_pk_fma_f32 v[46:47], v[94:95], v[46:47], v[126:127]
	s_waitcnt vmcnt(5)
	v_pk_fma_f32 v[36:37], v[100:101], v[36:37], v[132:133]
	v_pk_fma_f32 v[34:35], v[98:99], v[34:35], v[130:131]
	s_waitcnt vmcnt(4)
	v_pk_fma_f32 v[44:45], v[104:105], v[44:45], v[136:137]
	v_pk_fma_f32 v[42:43], v[102:103], v[42:43], v[134:135]
	s_waitcnt vmcnt(3)
	v_pk_fma_f32 v[56:57], v[56:57], v[108:109], v[140:141]
	v_pk_fma_f32 v[54:55], v[54:55], v[106:107], v[138:139]
	s_waitcnt vmcnt(2)
	v_pk_fma_f32 v[40:41], v[40:41], v[112:113], v[144:145]
	v_pk_fma_f32 v[38:39], v[38:39], v[110:111], v[142:143]
	s_waitcnt vmcnt(1)
	v_pk_fma_f32 v[60:61], v[60:61], v[116:117], v[148:149]
	v_pk_fma_f32 v[58:59], v[58:59], v[114:115], v[146:147]
	s_waitcnt vmcnt(0)
	v_pk_fma_f32 v[64:65], v[64:65], v[120:121], v[152:153]
	v_pk_fma_f32 v[62:63], v[62:63], v[118:119], v[150:151]
	v_cvt_pk_bf16_f32 v50, v50, v51
	v_cvt_pk_bf16_f32 v51, v52, v53
	v_cvt_pk_bf16_f32 v46, v46, v47
	v_cvt_pk_bf16_f32 v47, v48, v49
	v_cvt_pk_bf16_f32 v34, v34, v35
	v_cvt_pk_bf16_f32 v35, v36, v37
	v_cvt_pk_bf16_f32 v36, v42, v43
	v_cvt_pk_bf16_f32 v37, v44, v45
	v_cvt_pk_bf16_f32 v42, v54, v55
	v_cvt_pk_bf16_f32 v43, v56, v57
	v_cvt_pk_bf16_f32 v38, v38, v39
	v_cvt_pk_bf16_f32 v39, v40, v41
	v_cvt_pk_bf16_f32 v40, v58, v59
	v_cvt_pk_bf16_f32 v41, v60, v61
	v_cvt_pk_bf16_f32 v44, v62, v63
	v_cvt_pk_bf16_f32 v45, v64, v65
	global_store_dwordx2 v[72:73], v[50:51], off
	global_store_dwordx2 v[72:73], v[46:47], off offset:512
	global_store_dwordx2 v[72:73], v[34:35], off offset:1024
	global_store_dwordx2 v[72:73], v[36:37], off offset:1536
	global_store_dwordx2 v[72:73], v[42:43], off offset:2048
	global_store_dwordx2 v[72:73], v[38:39], off offset:2560
	global_store_dwordx2 v[72:73], v[40:41], off offset:3072
	global_store_dwordx2 v[72:73], v[44:45], off offset:3584
	v_lshl_add_u64 v[72:73], v[72:73], 0, s[10:11]
	s_andn2_b64 exec, exec, s[12:13]
	s_cbranch_execnz .LBB0_113
.LBB0_114:
	s_or_b64 exec, exec, s[4:5]
	s_cmp_eq_u32 s100, 0
	s_cbranch_scc1 .Ls0w_orig
	s_waitcnt vmcnt(0) lgkmcnt(0)
	s_barrier
	s_cmp_lg_u32 s94, 0
	s_cbranch_scc1 .Ls0w_join
	s_mov_b64 exec, 1
	v_mov_b32_e32 v4, 1
	v_mov_b32_e32 v8, 0
	s_and_b32 s6, s86, 7
	s_lshl_b32 s6, s6, 6
	s_add_u32 s6, s6, 0x6e20
	s_add_u32 s10, s60, s6
	s_addc_u32 s11, s61, 0
	s_add_u32 s8, s60, 0x6c80
	s_addc_u32 s9, s61, 0
	s_cmp_eq_u32 s100, 2
	s_cbranch_scc1 .Ls0w_arr
	buffer_wbl2 sc1
	s_waitcnt vmcnt(0)
.Ls0w_arr:
	global_atomic_add v8, v4, s[10:11]
	s_mov_b32 s16, 0
.Ls0w_g:
	global_load_dword v6, v8, s[10:11] sc1
	s_add_u32 s16, s16, 1
	s_waitcnt vmcnt(0)
	v_readfirstlane_b32 s15, v6
	s_cmp_ge_u32 s15, 32
	s_cbranch_scc1 .Ls0w_t
	s_sleep 1
	s_cmp_lt_u32 s16, 0x400000
	s_cbranch_scc1 .Ls0w_g

; __device__ __forceinline__ int opaque_tid(int wv) { unsigned z = 0u; asm volatile("" : "+v"(z)); return (wv << 6) | (int)__builtin_amdgcn_mbcnt_hi(~0u, __builtin_amdgcn_mbcnt_lo(~0u, z)); }
; #define SEAM(k) do { } while (0)
; #define SEAM(k) do { if (lo <= (k) && (k) + 1 < hi) { if (hi > 1000) grid.sync(); else xcd_barrier(xbar, xst, opaque_tid(wv) == 0); } } while (0)
; __global__ void __launch_bounds__(512) fwd_megakernel(Args A) {
;     ...
;     if (EN(0) && IN(0)) {
;         prologue_phase(A, lds, G, wv);
;         if (opaque_tid(wv) == 0) { unsigned sp = 0u; while (__hip_atomic_load((unsigned*)(ws + WS_CTL) + 4, __ATOMIC_RELAXED, __HIP_MEMORY_SCOPE_AGENT) < 384u && ++sp < (1u << 22)) __builtin_amdgcn_s_sleep(2); }
;         __syncthreads();
;         __builtin_amdgcn_fence(__ATOMIC_ACQUIRE, "agent");
;         norm_mod_phase(A.x, A.norm_mix, mod, mod + DM, Hb, G, wv);
;         SEAM(0);
.Ls0w_tp:
	global_load_dword v6, v8, s[8:9] sc1
	s_add_u32 s16, s16, 1
	s_waitcnt vmcnt(0)
	v_readfirstlane_b32 s15, v6
	s_cmp_ge_u32 s15, 8
	s_cbranch_scc1 .Ls0w_acq
	s_sleep 1
	s_cmp_lt_u32 s16, 0x400000
	s_cbranch_scc1 .Ls0w_tp

; #define LAS __attribute__((address_space(3)))
; __device__ __forceinline__ unsigned xb_ld(unsigned* p)              { return __hip_atomic_load(p, __ATOMIC_RELAXED, __HIP_MEMORY_SCOPE_AGENT); }
; __device__ __forceinline__ unsigned xb_add(unsigned* p, unsigned v) { return __hip_atomic_fetch_add(p, v, __ATOMIC_RELAXED, __HIP_MEMORY_SCOPE_AGENT); }
; __device__ __forceinline__ unsigned xb_xcc_id() { return (unsigned)__builtin_amdgcn_s_getreg((3 << 11) | 20) & 0xFu; }
; #define SEAM(k) do { } while (0)
; #define SEAM(k) do { if (lo <= (k) && (k) + 1 < hi) { if (hi > 1000) grid.sync(); else xcd_barrier(xbar, xst, opaque_tid(wv) == 0); } } while (0)
; __device__ __forceinline__ void xcd_barrier_complete(unsigned* bar, unsigned x, unsigned& nloc, unsigned& nx) {
;     const unsigned G = gridDim.x;
;     unsigned sum, cnt, mine, sp = 0u;
;     for (;;) {
;         sum = 0u; cnt = 0u; mine = 0u;
; #pragma unroll
;         for (unsigned j = 0; j < 16; ++j) { const unsigned c = xb_ld(&bar[XB_XCNT(j)]); sum += c; cnt += (c > 0u) ? 1u : 0u; mine = (j == x) ? c : mine; }
;         if (sum == G) break;
;         __builtin_amdgcn_s_sleep(1);
;         if ((++sp & 255u) == 0u) { if (xb_ld(&bar[XB_TMO])) break; if (sp > XB_SPIN_CAP) { atomicAdd(&bar[XB_TMO], 1u); break; } }
;     }
;     nloc = mine > 0u ? mine : 1u; nx = cnt > 0u ? cnt : 1u;
; }
; __device__ __forceinline__ void xcd_barrier(unsigned* bar, volatile LAS unsigned* st, bool is0) {
;     asm volatile("s_waitcnt vmcnt(0)" ::: "memory");
;     __syncthreads();
;     if (is0) {
;         __builtin_amdgcn_s_waitcnt(0);
;         const unsigned x = xb_xcc_id();
;         unsigned nloc = st[0], nx = st[1];
;         if (nloc == 0u) { xcd_barrier_complete(bar, x, nloc, nx); st[0] = nloc; st[1] = nx; }
;         const unsigned old = xb_add(&bar[XB_XSUB(x)], 1u);
; __global__ void __launch_bounds__(512) fwd_megakernel(Args A) {
;     ...
;         SEAM(0);
.Ls0w_join:
	s_barrier
	s_branch .LBB0_182
.Ls0w_orig:
	s_cmp_lt_i32 s63, 2
	s_cbranch_scc1 .LBB0_182
	s_cmpk_lt_u32 s63, 0x3e9
	s_mov_b64 s[0:1], -1
	s_cbranch_scc0 .LBB0_169
	v_mov_b32_e32 v2, 0
	s_waitcnt vmcnt(0)
	s_nop 0
	v_mbcnt_lo_u32_b32 v2, -1, v2
	v_mbcnt_hi_u32_b32 v2, -1, v2
	v_or_b32_e32 v2, s94, v2
	v_cmp_eq_u32_e32 vcc, 0, v2
	s_barrier
	s_and_saveexec_b64 s[0:1], vcc
	s_cbranch_execz .LBB0_168
	s_add_i32 s3, 0, 0x20040
	v_mov_b32_e32 v2, s3
	s_waitcnt vmcnt(0) expcnt(0) lgkmcnt(0)
	s_getreg_b32 s2, hwreg(HW_REG_XCC_ID, 0, 4)
	ds_read_b32 v4, v2
	s_add_i32 s3, 0, 0x20044
	v_mov_b32_e32 v2, s3
	ds_read_b32 v2, v2
	s_and_b32 s33, s2, 15
	s_waitcnt lgkmcnt(1)
	v_cmp_ne_u32_e32 vcc, 0, v4
	s_cbranch_vccnz .LBB0_132
	s_add_u32 s2, s60, 0x1200
	s_addc_u32 s3, s61, 0
	s_add_u32 s4, s60, 0x1400
	s_addc_u32 s5, s61, 0
	s_add_u32 s6, s60, 0x1500
	s_addc_u32 s7, s61, 0
	s_add_u32 s8, s60, 0x1600
	s_addc_u32 s9, s61, 0
	s_add_u32 s10, s60, 0x1700
	s_addc_u32 s11, s61, 0
	s_add_u32 s12, s60, 0x1800
	s_addc_u32 s13, s61, 0
	s_add_u32 s14, s60, 0x1900
	s_addc_u32 s15, s61, 0
	s_add_u32 s16, s60, 0x1a00
	s_addc_u32 s17, s61, 0
	s_add_u32 s18, s60, 0x1b00
	s_addc_u32 s19, s61, 0
	s_add_u32 s20, s60, 0x1c00
	s_addc_u32 s21, s61, 0
	s_add_u32 s22, s60, 0x1d00
	s_addc_u32 s23, s61, 0
	s_add_u32 s24, s60, 0x1e00
	s_addc_u32 s25, s61, 0
	s_add_u32 s26, s60, 0x1f00
	s_addc_u32 s27, s61, 0
	s_add_u32 s28, s60, 0x2000
	s_addc_u32 s29, s61, 0
	s_add_u32 s30, s60, 0x2100
	s_addc_u32 s31, s61, 0
	s_add_u32 s34, s60, 0x2200
	s_addc_u32 s35, s61, 0
	s_add_u32 s36, s60, 0x2300
	s_addc_u32 s37, s61, 0
	s_mov_b32 s44, 1
	v_mov_b32_e32 v18, 0
	s_branch .LBB0_120
